# final-phase y_sample stores write-through as well
# speedup vs baseline: 1.0331x; 1.0225x over previous
.LBB0_731:
	s_or_b64 exec, exec, s[4:5]
	s_waitcnt lgkmcnt(0)
	s_barrier
	global_load_dwordx4 v[24:27], v[12:13], off
	ds_read_b64 v[20:21], v73
	v_add_u32_e32 v28, 0x2400, v75
	v_ashrrev_i32_e32 v29, 31, v28
	s_addk_i32 s6, 0x400
	v_add_u32_e32 v72, 0x40000, v72
	s_waitcnt lgkmcnt(0)
	v_add_f32_e32 v8, v20, v21
	v_fmamk_f32 v8, v8, 0x3a000000, v74
	v_mul_f32_e32 v20, 0x4b800000, v8
	v_cmp_gt_f32_e32 vcc, s8, v8
	s_cmp_lt_i32 s6, 0
	v_lshl_add_u64 v[16:17], v[16:17], 0, s[2:3]
	v_cndmask_b32_e32 v8, v8, v20, vcc
	v_rsq_f32_e32 v8, v8
	v_lshlrev_b64 v[20:21], 13, v[28:29]
	v_lshl_add_u64 v[28:29], v[14:15], 0, v[20:21]
	v_mul_f32_e32 v20, 0x45800000, v8
	v_cndmask_b32_e32 v8, v8, v20, vcc
	v_pk_mul_f32 v[22:23], v[8:9], v[22:23] op_sel_hi:[0,1]
	v_pk_mul_f32 v[18:19], v[8:9], v[18:19] op_sel_hi:[0,1]
	s_waitcnt vmcnt(0)
	v_pk_mul_f32 v[20:21], v[18:19], v[26:27]
	v_pk_mul_f32 v[18:19], v[22:23], v[24:25]
	global_store_dwordx4 v[28:29], v[18:21], off sc1
	global_load_dwordx4 v[18:21], v[12:13], off offset:1024
	v_pk_mul_f32 v[22:23], v[8:9], v[4:5] op_sel_hi:[0,1]
	v_pk_mul_f32 v[4:5], v[8:9], v[6:7] op_sel_hi:[0,1]
	s_waitcnt vmcnt(0)
	v_pk_mul_f32 v[4:5], v[4:5], v[18:19]
	v_pk_mul_f32 v[6:7], v[22:23], v[20:21]
	global_store_dwordx4 v[28:29], v[4:7], off offset:1024 sc1
	global_load_dwordx4 v[4:7], v[12:13], off offset:2048
	v_pk_mul_f32 v[18:19], v[8:9], v[36:37] op_sel_hi:[0,1]
	v_pk_mul_f32 v[20:21], v[8:9], v[38:39] op_sel_hi:[0,1]
	s_waitcnt vmcnt(0)
	v_pk_mul_f32 v[4:5], v[20:21], v[4:5]
	v_pk_mul_f32 v[6:7], v[18:19], v[6:7]
	global_store_dwordx4 v[28:29], v[4:7], off offset:2048 sc1
	global_load_dwordx4 v[4:7], v[12:13], off offset:3072
	v_pk_mul_f32 v[18:19], v[8:9], v[0:1] op_sel_hi:[0,1]
	v_pk_mul_f32 v[0:1], v[8:9], v[2:3] op_sel_hi:[0,1]
	s_waitcnt vmcnt(0)
	v_pk_mul_f32 v[0:1], v[0:1], v[4:5]
	v_pk_mul_f32 v[2:3], v[18:19], v[6:7]
	global_store_dwordx4 v[28:29], v[0:3], off offset:3072 sc1
	s_barrier
	s_cbranch_scc0 .LBB0_734
